# g1 unit loop: counted vmcnt wait (16 S stores may stay in flight) instead of vmcnt(0) before the gate computation, first iteration unchanged
# speedup vs baseline: 1.0090x; 1.0070x over previous
; #define LAS __attribute__((address_space(3)))
; __device__ __forceinline__ void gates_load(const Args& a, int m0, int h, int tid, GateIn& g) {
;     const float* alr = (const float*)(a.ws + WS_ALR) + (size_t)m0 * 16;
;     g.av = (f32x4){0.f, 0.f, 0.f, 0.f};
;     if (tid < 256) g.av = *(const f32x4*)(alr + 4 * tid);
;     const int d = tid & 127;
; #pragma unroll
;     for (int r = 0; r < 16; ++r) g.w2r[r] = a.in[I_GW2][r * 512 + h * 128 + d];
;     g.gb = a.in[I_GB][h * 128 + d];
; }
; __device__ __forceinline__ void phase_g1(const Args& a, LAS unsigned char* lds, int tid, int lane, int wave) {
;     LAS float* aL = (LAS float*)lds; LAS float* tot = (LAS float*)(lds + 4096); LAS bf16* kdT = (LAS bf16*)(lds + 8192);
;     LAS bf16* Kr = (LAS bf16*)(lds + 26624); LAS bf16* Vs = (LAS bf16*)(lds + 44032);
;     const bf16* proj = (const bf16*)(a.ws + WS_PROJ); bf16* S = (bf16*)(a.ws + WS_S); float* dec = (float*)(a.ws + WS_DEC);
;     const int d = tid & 127, ig = tid >> 7, r16 = lane & 15, q4 = lane >> 4;
;     GateIn gin; v4u kreg[2], vreg[4];
;     ...
;     if ((int)blockIdx.x < 2048) G1_LOADS((int)blockIdx.x);
;     for (int unit = blockIdx.x; unit < 2048; unit += gridDim.x) {
.LBB0_282:
	s_or_b64 exec, exec, s[8:9]
	v_add_u32_e32 v1, 0x600, v175
	v_lshrrev_b32_e32 v50, 5, v1
	s_add_u32 s24, s80, 0x2ea00000
	v_add_u32_e32 v1, s6, v50
	s_movk_i32 s38, 0x3000
	v_mov_b64_e32 v[6:7], s[20:21]
	s_addc_u32 s25, s81, 0
	s_bfe_u32 s7, s2, 0x20008
	v_mad_i64_i32 v[8:9], s[8:9], v1, s38, v[6:7]
	v_lshlrev_b32_e32 v1, 3, v175
	v_lshrrev_b32_e32 v51, 5, v175
	s_lshl_b32 s8, s7, 9
	s_mov_b32 s9, s23
	v_and_b32_e32 v42, 0xf8, v1
	v_or_b32_e32 v14, s6, v51
	v_lshl_add_u64 v[8:9], v[8:9], 0, s[8:9]
	v_lshlrev_b32_e32 v32, 1, v42
	v_mov_b32_e32 v33, v0
	v_or_b32_e32 v10, 32, v14
	v_add_u32_e32 v16, 0x200, v175
	v_lshl_add_u64 v[8:9], v[8:9], 0, v[32:33]
	v_mad_i64_i32 v[10:11], s[10:11], v10, s38, v[6:7]
	v_lshrrev_b32_e32 v52, 5, v16
	s_movk_i32 s39, 0x2000
	v_lshl_add_u64 v[10:11], v[10:11], 0, s[8:9]
	v_or_b32_e32 v12, s6, v52
	v_add_co_u32_e32 v8, vcc, s39, v8
	v_lshl_add_u64 v[10:11], v[10:11], 0, v[32:33]
	v_mad_i64_i32 v[12:13], s[10:11], v12, s38, v[6:7]
	v_addc_co_u32_e32 v9, vcc, 0, v9, vcc
	v_lshl_add_u64 v[12:13], v[12:13], 0, s[8:9]
	v_lshrrev_b32_e32 v53, 4, v16
	v_add_co_u32_e32 v10, vcc, s39, v10
	v_lshl_add_u64 v[12:13], v[12:13], 0, v[32:33]
	v_mad_i64_i32 v[14:15], s[10:11], v14, s38, v[6:7]
	v_add_u32_e32 v16, s6, v53
	v_addc_co_u32_e32 v11, vcc, 0, v11, vcc
	s_lshl_b32 s22, s7, 8
	v_lshl_add_u64 v[14:15], v[14:15], 0, s[8:9]
	v_mad_i64_i32 v[16:17], s[10:11], v16, s38, v[6:7]
	v_and_b32_e32 v40, 0x78, v1
	global_load_dwordx4 v[22:25], v[8:9], off
	global_load_dwordx4 v[26:29], v[10:11], off
	v_add_co_u32_e32 v8, vcc, s39, v12
	v_lshl_add_u64 v[14:15], v[14:15], 0, v[32:33]
	v_lshl_add_u64 v[16:17], v[16:17], 0, s[22:23]
	v_lshlrev_b32_e32 v34, 1, v40
	v_mov_b32_e32 v35, v0
	v_lshrrev_b32_e32 v54, 4, v175
	v_addc_co_u32_e32 v9, vcc, 0, v13, vcc
	v_lshl_add_u64 v[38:39], v[16:17], 0, v[34:35]
	v_or_b32_e32 v16, s6, v54
	v_add_co_u32_e32 v10, vcc, s39, v14
	v_mad_i64_i32 v[6:7], s[6:7], v16, s38, v[6:7]
	v_lshlrev_b32_e32 v16, 2, v48
	v_addc_co_u32_e32 v11, vcc, 0, v15, vcc
	s_movk_i32 s40, 0x1000
	v_lshl_add_u64 v[6:7], v[6:7], 0, s[22:23]
	v_or_b32_e32 v44, s8, v16
	v_add_u32_e32 v57, 0, v16
	global_load_dwordx4 v[14:17], v[8:9], off
	global_load_dwordx4 v[18:21], v[10:11], off
	v_add_co_u32_e32 v8, vcc, s40, v38
	v_lshl_add_u64 v[6:7], v[6:7], 0, v[34:35]
	s_nop 0
	v_addc_co_u32_e32 v9, vcc, 0, v39, vcc
	v_mov_b32_e32 v45, v0
	v_add_co_u32_e32 v10, vcc, s40, v6
	v_lshl_add_u64 v[46:47], s[60:61], 0, v[44:45]
	s_nop 0
	v_addc_co_u32_e32 v11, vcc, 0, v7, vcc
	s_movk_i32 s41, 0x7000
	v_add_co_u32_e32 v38, vcc, s41, v46
	s_movk_i32 s42, 0x6000
	s_nop 0
	v_addc_co_u32_e32 v39, vcc, 0, v47, vcc
	v_add_co_u32_e32 v58, vcc, s42, v46
	s_movk_i32 s43, 0x5000
	s_nop 0
	v_addc_co_u32_e32 v59, vcc, 0, v47, vcc
	v_add_co_u32_e32 v64, vcc, s43, v46
	s_movk_i32 s46, 0x4000
	s_nop 0
	v_addc_co_u32_e32 v65, vcc, 0, v47, vcc
	v_add_co_u32_e32 v66, vcc, s46, v46
	v_and_b32_e32 v1, 0x1c00, v1
	s_nop 0
	v_addc_co_u32_e32 v67, vcc, 0, v47, vcc
	v_add_u32_e32 v55, 0, v1
	global_load_dwordx4 v[6:9], v[8:9], off offset:3072
	s_nop 0
	global_load_dwordx4 v[10:13], v[10:11], off offset:3072
	s_nop 0
	global_load_dword v62, v[38:39], off offset:2048
	global_load_dword v60, v[58:59], off offset:2048
	global_load_dword v61, v[64:65], off offset:2048
	global_load_dword v1, v[66:67], off offset:2048
	s_nop 0
	global_load_dword v66, v[66:67], off
	s_nop 0
	global_load_dword v69, v[64:65], off
	global_load_dword v63, v[58:59], off
	s_nop 0
	global_load_dword v65, v[38:39], off
	v_add_co_u32_e32 v38, vcc, s38, v46
	v_lshlrev_b32_e32 v31, 1, v48
	s_nop 0
	v_addc_co_u32_e32 v39, vcc, 0, v47, vcc
	v_add_co_u32_e32 v58, vcc, s39, v46
	v_add_u32_e32 v43, 0, v32
	s_nop 0
	v_addc_co_u32_e32 v59, vcc, 0, v47, vcc
	v_add_co_u32_e32 v46, vcc, s40, v46
	v_lshrrev_b32_e32 v32, 2, v174
	s_nop 0
	v_addc_co_u32_e32 v47, vcc, 0, v47, vcc
	global_load_dword v82, v[38:39], off offset:2048
	global_load_dword v72, v[58:59], off offset:2048
	global_load_dword v75, v[46:47], off offset:2048
	global_load_dword v74, v[46:47], off
	global_load_dword v83, v[58:59], off
	global_load_dword v86, v[38:39], off
	global_load_dword v87, v44, s[62:63]
	global_load_dword v85, v44, s[60:61] offset:2048
	global_load_dword v84, v44, s[60:61]
	v_sub_u32_e32 v44, v57, v31
	v_lshrrev_b32_e32 v31, 1, v175
	v_and_b32_e32 v31, 24, v31
	s_movk_i32 s22, 0x8e
	v_and_or_b32 v31, v32, 3, v31
	v_mad_u32_u24 v45, v48, s22, v44
	v_mul_u32_u24_e32 v31, 0x108, v31
	s_lshl_b32 s22, s3, 5
	v_and_b32_e32 v30, 12, v30
	s_load_dword s47, s[18:19], 0x0
	v_add3_u32 v30, v31, v30, s22
	s_add_i32 s26, 0, 0xac00
	v_and_b32_e32 v37, 15, v175
	v_lshl_add_u32 v58, v30, 1, s26
	v_and_b32_e32 v30, 48, v175
	v_add_u32_e32 v47, 0, v30
	v_or_b32_e32 v32, s22, v37
	v_lshrrev_b32_e32 v30, 1, v174
	v_or_b32_e32 v33, 48, v174
	v_and_b32_e32 v30, 24, v30
	v_mov_b32_e32 v31, v0
	v_mul_u32_u24_e32 v78, 0x90, v37
	v_mul_u32_u24_e32 v79, 0x90, v33
	v_or_b32_e32 v33, 0x70, v174
	v_lshlrev_b32_e32 v32, 7, v32
	v_mov_b32_e32 v37, v0
	v_lshlrev_b32_e32 v41, 4, v175
	s_movk_i32 s6, 0x80
	s_movk_i32 s8, 0xff
	s_movk_i32 s10, 0x17f
	s_movk_i32 s12, 0x1ff
	v_add_u32_e32 v39, 0, v34
	v_lshlrev_b32_e32 v46, 5, v49
	v_lshl_add_u64 v[30:31], s[80:81], 0, v[30:31]
	s_mov_b64 s[26:27], 0x26a00000
	v_mul_u32_u24_e32 v67, 0x110, v54
	v_mul_u32_u24_e32 v68, 0x110, v53
	v_mul_u32_u24_e32 v70, 0x210, v51
	v_mul_u32_u24_e32 v71, 0x210, v52
	v_mul_u32_u24_e32 v73, 0x210, v50
	v_mul_u32_u24_e32 v76, 0x1100, v49
	v_mul_u32_u24_e32 v80, 0x90, v33
	v_or_b32_e32 v34, 0x800, v32
	v_lshl_add_u64 v[36:37], s[14:15], 0, v[36:37]
	s_waitcnt lgkmcnt(0)
	s_add_i32 s14, s2, s47
	v_lshl_add_u32 v56, v175, 2, 0
	v_cmp_gt_u32_e64 s[6:7], s6, v175
	v_cmp_lt_u32_e64 s[8:9], s8, v175
	v_cmp_lt_u32_e64 s[10:11], s10, v175
	v_cmp_lt_u32_e64 s[12:13], s12, v175
	v_lshl_add_u64 v[30:31], v[30:31], 0, s[26:27]
	v_or_b32_e32 v59, 32, v51
	v_ashrrev_i32_e32 v33, 31, v32
	v_ashrrev_i32_e32 v35, 31, v34
	v_lshl_add_u32 v38, s2, 7, v175
	s_lshl_b32 s48, s47, 7
	s_lshl_b32 s49, s14, 4
	s_lshl_b32 s50, s47, 4
	s_lshl_b32 s51, s14, 6
	s_lshl_b32 s52, s47, 6
	v_add_u32_e32 v64, 0, v41
	s_mov_b32 s53, 0xbfb8aa3b
	s_mov_b32 s56, 0x800000
	s_mov_b32 s57, 0x3f317217
	s_mov_b32 s67, 0x7f800000
	s_mov_b32 s72, 0x3d800000
	v_add_u32_e32 v67, v39, v67
	v_add_u32_e32 v68, v39, v68
	v_add_u32_e32 v70, v43, v70
	v_add_u32_e32 v71, v43, v71
	v_add_u32_e32 v73, v43, v73
	v_lshlrev_b32_e32 v40, 1, v40
	v_lshlrev_b32_e32 v42, 1, v42
	v_add_u32_e32 v76, v44, v76
	v_add_u32_e32 v77, v45, v46
	v_add_u32_e32 v78, v47, v78
	v_add_u32_e32 v79, v47, v79
	v_add_u32_e32 v80, v47, v80
	v_mov_b32_e32 v81, 0x41b17218
	s_mov_b32 s26, s2
	s_mov_b32 s98, 0
	s_branch .LBB0_284

; #define LAS __attribute__((address_space(3)))
; __device__ __forceinline__ void gates_compute(const GateIn& g, LAS float* aL, LAS float* tot, int tid, float (&bq)[16], float& blast) {
;     if (tid < 256) *(LAS f32x4*)(aL + 4 * tid) = g.av;
;     const int d = tid & 127, ig = tid >> 7;
;     __syncthreads();
;     float run = 0.f;
; #pragma unroll
;     for (int ii = 0; ii < 16; ++ii) { const LAS f32x4* ar = (const LAS f32x4*)(aL + (16 * ig + ii) * 16); float z = g.gb;
; #pragma unroll
;         for (int r4 = 0; r4 < 4; ++r4) { const f32x4 av = ar[r4]; z += av.x * g.w2r[4 * r4] + av.y * g.w2r[4 * r4 + 1] + av.z * g.w2r[4 * r4 + 2] + av.w * g.w2r[4 * r4 + 3]; }
;         const float ls = fminf(z, 0.f) - __logf(1.0f + __expf(-fabsf(z)));
;         run += ls * (1.0f / 16.0f); bq[ii] = run; }
.LBB0_286:
	s_or_b64 exec, exec, s[14:15]
	s_waitcnt lgkmcnt(0)
	s_barrier
	ds_read_b128 v[44:47], v55
	ds_read_b128 v[88:91], v55 offset:16
	ds_read_b128 v[92:95], v55 offset:32
	ds_read_b128 v[96:99], v55 offset:48
	s_add_i32 s73, s26, s47
	s_cmp_eq_u32 s98, 0
	s_cbranch_scc1 .Lg1w_first
	s_waitcnt vmcnt(16) lgkmcnt(3)
	s_branch .Lg1w_done
.Lg1w_first:
	s_waitcnt vmcnt(0) lgkmcnt(3)
	s_mov_b32 s98, 1
.Lg1w_done:
	v_mul_f32_e32 v39, v85, v45
	s_nop 0
	v_fmac_f32_e32 v39, v84, v44
	s_waitcnt lgkmcnt(2)
	v_mul_f32_e32 v41, v72, v89
	v_fmac_f32_e32 v39, v74, v46
	v_fmac_f32_e32 v41, v83, v88
	v_fmac_f32_e32 v39, v75, v47
	v_fmac_f32_e32 v41, v86, v90
	v_add_f32_e32 v39, v87, v39
	v_fmac_f32_e32 v41, v82, v91
	ds_read_b128 v[44:47], v55 offset:64
	ds_read_b128 v[88:91], v55 offset:80
	v_add_f32_e32 v39, v39, v41
	s_waitcnt lgkmcnt(3)
	v_mul_f32_e32 v41, v1, v93
	v_fmac_f32_e32 v41, v66, v92
	v_fmac_f32_e32 v41, v69, v94
	v_fmac_f32_e32 v41, v61, v95
	v_add_f32_e32 v39, v39, v41
	s_waitcnt lgkmcnt(2)
	v_mul_f32_e32 v41, v60, v97
	s_waitcnt lgkmcnt(1)
	v_mul_f32_e32 v45, v85, v45
	v_fmac_f32_e32 v41, v63, v96
	v_fmac_f32_e32 v45, v84, v44
	v_fmac_f32_e32 v41, v65, v98
	v_fmac_f32_e32 v45, v74, v46
	v_fmac_f32_e32 v41, v62, v99
	v_fmac_f32_e32 v45, v75, v47
	v_add_f32_e32 v39, v39, v41
	v_add_f32_e32 v92, v87, v45
	s_waitcnt lgkmcnt(0)
	v_mul_f32_e32 v89, v72, v89
	ds_read_b128 v[44:47], v55 offset:96
	v_mul_f32_e64 v41, |v39|, s53
	v_fmac_f32_e32 v89, v83, v88
	v_exp_f32_e32 v41, v41
	v_fmac_f32_e32 v89, v86, v90
	v_fmac_f32_e32 v89, v82, v91
	v_add_f32_e32 v92, v92, v89
	ds_read_b128 v[88:91], v55 offset:112
	s_waitcnt lgkmcnt(1)
	v_mul_f32_e32 v45, v1, v45
	v_add_f32_e32 v41, 1.0, v41
	v_fmac_f32_e32 v45, v66, v44
	v_cmp_gt_f32_e32 vcc, s56, v41
	v_fmac_f32_e32 v45, v69, v46
	v_fmac_f32_e32 v45, v61, v47
	v_cndmask_b32_e64 v43, 0, 32, vcc
	v_ldexp_f32 v41, v41, v43
	v_add_f32_e32 v44, v92, v45
	s_waitcnt lgkmcnt(0)
	v_mul_f32_e32 v45, v60, v89
	v_log_f32_e32 v41, v41
	v_fmac_f32_e32 v45, v63, v88
	v_fmac_f32_e32 v45, v65, v90
	v_fmac_f32_e32 v45, v62, v91
	v_add_f32_e32 v44, v44, v45
	v_mul_f32_e32 v43, 0x3f317217, v41
	v_mul_f32_e64 v45, |v44|, s53
	v_fma_f32 v43, v41, s57, -v43
	v_exp_f32_e32 v45, v45
	v_fmac_f32_e32 v43, 0x3377d1cf, v41
	v_fmac_f32_e32 v43, 0x3f317217, v41
	v_cmp_lt_f32_e64 s[14:15], |v41|, s67
	v_min_f32_e32 v39, 0, v39
	s_cmpk_gt_i32 s73, 0x7ff
	v_cndmask_b32_e64 v41, v41, v43, s[14:15]
	v_cndmask_b32_e32 v43, 0, v81, vcc
	v_sub_f32_e32 v41, v41, v43
	v_add_f32_e32 v43, 1.0, v45
	v_cmp_gt_f32_e32 vcc, s56, v43
	v_sub_f32_e32 v39, v39, v41
	v_min_f32_e32 v41, 0, v44
	v_cndmask_b32_e64 v45, 0, 32, vcc
	v_ldexp_f32 v43, v43, v45
	v_log_f32_e32 v43, v43
	ds_read_b128 v[44:47], v55 offset:128
	v_fma_f32 v39, v39, s72, 0
	v_mul_f32_e32 v88, 0x3f317217, v43
	v_fma_f32 v92, v43, s57, -v88
	ds_read_b128 v[88:91], v55 offset:144
	s_waitcnt lgkmcnt(1)
	v_mul_f32_e32 v45, v85, v45
	v_fmac_f32_e32 v45, v84, v44
	v_fmac_f32_e32 v45, v74, v46
	v_fmac_f32_e32 v45, v75, v47
	v_add_f32_e32 v93, v87, v45
	s_waitcnt lgkmcnt(0)
	v_mul_f32_e32 v89, v72, v89
	ds_read_b128 v[44:47], v55 offset:160
	v_fmac_f32_e32 v89, v83, v88
	v_fmac_f32_e32 v89, v86, v90
	v_fmac_f32_e32 v89, v82, v91
	v_add_f32_e32 v93, v93, v89
	ds_read_b128 v[88:91], v55 offset:176
	s_waitcnt lgkmcnt(1)
	v_mul_f32_e32 v45, v1, v45
	v_fmac_f32_e32 v45, v66, v44
	v_fmac_f32_e32 v45, v69, v46
	v_fmac_f32_e32 v45, v61, v47
	v_add_f32_e32 v44, v93, v45
	s_waitcnt lgkmcnt(0)
	v_mul_f32_e32 v45, v60, v89
	v_fmac_f32_e32 v45, v63, v88
	v_fmac_f32_e32 v45, v65, v90
	v_fmac_f32_e32 v45, v62, v91
	v_add_f32_e32 v44, v44, v45
	v_mul_f32_e64 v45, |v44|, s53
	v_exp_f32_e32 v45, v45
	v_fmac_f32_e32 v92, 0x3377d1cf, v43
	v_fmac_f32_e32 v92, 0x3f317217, v43
	v_cmp_lt_f32_e64 s[14:15], |v43|, s67
	v_add_f32_e32 v45, 1.0, v45
	v_cndmask_b32_e32 v46, 0, v81, vcc
	v_cndmask_b32_e64 v43, v43, v92, s[14:15]
	v_cmp_gt_f32_e32 vcc, s56, v45
	v_sub_f32_e32 v43, v43, v46
	v_sub_f32_e32 v41, v41, v43
	v_cndmask_b32_e64 v46, 0, 32, vcc
	v_ldexp_f32 v45, v45, v46
	v_log_f32_e32 v89, v45
	v_fmamk_f32 v88, v41, 0x3d800000, v39
	v_min_f32_e32 v41, 0, v44
	ds_read_b128 v[44:47], v55 offset:192
	ds_read_b128 v[90:93], v55 offset:208
	v_mul_f32_e32 v43, 0x3f317217, v89
	v_fma_f32 v43, v89, s57, -v43
	v_fmac_f32_e32 v43, 0x3377d1cf, v89
	s_waitcnt lgkmcnt(1)
	v_mul_f32_e32 v45, v85, v45
	v_fmac_f32_e32 v45, v84, v44
	v_fmac_f32_e32 v45, v74, v46
	v_fmac_f32_e32 v45, v75, v47
	v_add_f32_e32 v94, v87, v45
	s_waitcnt lgkmcnt(0)
	v_mul_f32_e32 v91, v72, v91
	ds_read_b128 v[44:47], v55 offset:224
	v_fmac_f32_e32 v91, v83, v90
	v_fmac_f32_e32 v91, v86, v92
	v_fmac_f32_e32 v91, v82, v93
	v_add_f32_e32 v94, v94, v91
	ds_read_b128 v[90:93], v55 offset:240
	s_waitcnt lgkmcnt(1)
	v_mul_f32_e32 v45, v1, v45
	v_fmac_f32_e32 v45, v66, v44
	v_fmac_f32_e32 v45, v69, v46
	v_fmac_f32_e32 v45, v61, v47
	v_add_f32_e32 v44, v94, v45
	s_waitcnt lgkmcnt(0)
	v_mul_f32_e32 v45, v60, v91
	v_fmac_f32_e32 v45, v63, v90
	v_fmac_f32_e32 v45, v65, v92
	v_fmac_f32_e32 v45, v62, v93
	v_add_f32_e32 v44, v44, v45
	v_mul_f32_e64 v45, |v44|, s53
	v_exp_f32_e32 v45, v45
	v_fmac_f32_e32 v43, 0x3f317217, v89
	v_cmp_lt_f32_e64 s[14:15], |v89|, s67
	v_cndmask_b32_e32 v46, 0, v81, vcc
	v_add_f32_e32 v45, 1.0, v45
	v_cndmask_b32_e64 v43, v89, v43, s[14:15]
	v_cmp_gt_f32_e32 vcc, s56, v45
	v_sub_f32_e32 v43, v43, v46
	v_sub_f32_e32 v41, v41, v43
	v_cndmask_b32_e64 v46, 0, 32, vcc
	v_ldexp_f32 v45, v45, v46
	v_log_f32_e32 v94, v45
	v_fmamk_f32 v89, v41, 0x3d800000, v88
	v_min_f32_e32 v41, 0, v44
	ds_read_b128 v[44:47], v55 offset:256
	ds_read_b128 v[90:93], v55 offset:272
	v_mul_f32_e32 v43, 0x3f317217, v94
	v_fma_f32 v43, v94, s57, -v43
	v_fmac_f32_e32 v43, 0x3377d1cf, v94
	s_waitcnt lgkmcnt(1)
; #define LAS __attribute__((address_space(3)))
; __device__ __forceinline__ void gates_compute(const GateIn& g, LAS float* aL, LAS float* tot, int tid, float (&bq)[16], float& blast) {
;     ...
;     float run = 0.f;
; #pragma unroll
;     for (int ii = 0; ii < 16; ++ii) { const LAS f32x4* ar = (const LAS f32x4*)(aL + (16 * ig + ii) * 16); float z = g.gb;
; #pragma unroll
;         for (int r4 = 0; r4 < 4; ++r4) { const f32x4 av = ar[r4]; z += av.x * g.w2r[4 * r4] + av.y * g.w2r[4 * r4 + 1] + av.z * g.w2r[4 * r4 + 2] + av.w * g.w2r[4 * r4 + 3]; }
;         const float ls = fminf(z, 0.f) - __logf(1.0f + __expf(-fabsf(z)));
;         run += ls * (1.0f / 16.0f); bq[ii] = run; }
	v_mul_f32_e32 v45, v85, v45
	v_fmac_f32_e32 v45, v84, v44
	v_fmac_f32_e32 v45, v74, v46
	v_fmac_f32_e32 v45, v75, v47
	v_add_f32_e32 v95, v87, v45
	s_waitcnt lgkmcnt(0)
	v_mul_f32_e32 v91, v72, v91
	ds_read_b128 v[44:47], v55 offset:288
	v_fmac_f32_e32 v91, v83, v90
	v_fmac_f32_e32 v91, v86, v92
	v_fmac_f32_e32 v91, v82, v93
	v_add_f32_e32 v95, v95, v91
	ds_read_b128 v[90:93], v55 offset:304
	s_waitcnt lgkmcnt(1)
	v_mul_f32_e32 v45, v1, v45
	v_fmac_f32_e32 v45, v66, v44
	v_fmac_f32_e32 v45, v69, v46
	v_fmac_f32_e32 v45, v61, v47
	v_add_f32_e32 v44, v95, v45
	s_waitcnt lgkmcnt(0)
	v_mul_f32_e32 v45, v60, v91
	v_fmac_f32_e32 v45, v63, v90
	v_fmac_f32_e32 v45, v65, v92
	v_fmac_f32_e32 v45, v62, v93
	v_add_f32_e32 v44, v44, v45
	v_mul_f32_e64 v45, |v44|, s53
	v_exp_f32_e32 v45, v45
	v_fmac_f32_e32 v43, 0x3f317217, v94
	v_cmp_lt_f32_e64 s[14:15], |v94|, s67
	v_cndmask_b32_e32 v46, 0, v81, vcc
	v_add_f32_e32 v45, 1.0, v45
	v_cndmask_b32_e64 v43, v94, v43, s[14:15]
	v_cmp_gt_f32_e32 vcc, s56, v45
	v_sub_f32_e32 v43, v43, v46
	v_sub_f32_e32 v41, v41, v43
	v_cndmask_b32_e64 v46, 0, 32, vcc
	v_ldexp_f32 v45, v45, v46
	v_log_f32_e32 v91, v45
	v_fmamk_f32 v90, v41, 0x3d800000, v89
	v_min_f32_e32 v41, 0, v44
	ds_read_b128 v[44:47], v55 offset:320
	ds_read_b128 v[92:95], v55 offset:336
	v_mul_f32_e32 v43, 0x3f317217, v91
	v_fma_f32 v43, v91, s57, -v43
	v_fmac_f32_e32 v43, 0x3377d1cf, v91
	s_waitcnt lgkmcnt(1)
	v_mul_f32_e32 v45, v85, v45
	v_fmac_f32_e32 v45, v84, v44
	v_fmac_f32_e32 v45, v74, v46
	v_fmac_f32_e32 v45, v75, v47
	v_add_f32_e32 v96, v87, v45
	s_waitcnt lgkmcnt(0)
	v_mul_f32_e32 v93, v72, v93
	ds_read_b128 v[44:47], v55 offset:352
	v_fmac_f32_e32 v93, v83, v92
	v_fmac_f32_e32 v93, v86, v94
	v_fmac_f32_e32 v93, v82, v95
	v_add_f32_e32 v96, v96, v93
	ds_read_b128 v[92:95], v55 offset:368
	s_waitcnt lgkmcnt(1)
	v_mul_f32_e32 v45, v1, v45
	v_fmac_f32_e32 v45, v66, v44
	v_fmac_f32_e32 v45, v69, v46
	v_fmac_f32_e32 v45, v61, v47
	v_add_f32_e32 v44, v96, v45
	s_waitcnt lgkmcnt(0)
	v_mul_f32_e32 v45, v60, v93
	v_fmac_f32_e32 v45, v63, v92
	v_fmac_f32_e32 v45, v65, v94
	v_fmac_f32_e32 v45, v62, v95
	v_add_f32_e32 v44, v44, v45
	v_mul_f32_e64 v45, |v44|, s53
	v_exp_f32_e32 v45, v45
	v_fmac_f32_e32 v43, 0x3f317217, v91
	v_cmp_lt_f32_e64 s[14:15], |v91|, s67
	v_cndmask_b32_e32 v46, 0, v81, vcc
	v_add_f32_e32 v45, 1.0, v45
	v_cndmask_b32_e64 v43, v91, v43, s[14:15]
	v_cmp_gt_f32_e32 vcc, s56, v45
	v_sub_f32_e32 v43, v43, v46
	v_sub_f32_e32 v41, v41, v43
	v_cndmask_b32_e64 v46, 0, 32, vcc
	v_ldexp_f32 v45, v45, v46
	v_log_f32_e32 v96, v45
	v_fmamk_f32 v91, v41, 0x3d800000, v90
	v_min_f32_e32 v41, 0, v44
	ds_read_b128 v[44:47], v55 offset:384
	ds_read_b128 v[92:95], v55 offset:400
	v_mul_f32_e32 v43, 0x3f317217, v96
	v_fma_f32 v43, v96, s57, -v43
	v_fmac_f32_e32 v43, 0x3377d1cf, v96
	s_waitcnt lgkmcnt(1)
	v_mul_f32_e32 v45, v85, v45
	v_fmac_f32_e32 v45, v84, v44
	v_fmac_f32_e32 v45, v74, v46
	v_fmac_f32_e32 v45, v75, v47
	v_add_f32_e32 v97, v87, v45
	s_waitcnt lgkmcnt(0)
	v_mul_f32_e32 v93, v72, v93
	ds_read_b128 v[44:47], v55 offset:416
	v_fmac_f32_e32 v93, v83, v92
	v_fmac_f32_e32 v93, v86, v94
	v_fmac_f32_e32 v93, v82, v95
	v_add_f32_e32 v97, v97, v93
	ds_read_b128 v[92:95], v55 offset:432
	s_waitcnt lgkmcnt(1)
	v_mul_f32_e32 v45, v1, v45
	v_fmac_f32_e32 v45, v66, v44
	v_fmac_f32_e32 v45, v69, v46
	v_fmac_f32_e32 v45, v61, v47
	v_add_f32_e32 v44, v97, v45
	s_waitcnt lgkmcnt(0)
	v_mul_f32_e32 v45, v60, v93
	v_fmac_f32_e32 v45, v63, v92
	v_fmac_f32_e32 v45, v65, v94
	v_fmac_f32_e32 v45, v62, v95
	v_add_f32_e32 v44, v44, v45
	v_mul_f32_e64 v45, |v44|, s53
	v_exp_f32_e32 v45, v45
	v_fmac_f32_e32 v43, 0x3f317217, v96
	v_cmp_lt_f32_e64 s[14:15], |v96|, s67
	v_cndmask_b32_e32 v46, 0, v81, vcc
	v_add_f32_e32 v45, 1.0, v45
	v_cndmask_b32_e64 v43, v96, v43, s[14:15]
	v_cmp_gt_f32_e32 vcc, s56, v45
	v_sub_f32_e32 v43, v43, v46
	v_sub_f32_e32 v41, v41, v43
	v_cndmask_b32_e64 v46, 0, 32, vcc
	v_ldexp_f32 v45, v45, v46
	v_log_f32_e32 v93, v45
	v_fmamk_f32 v92, v41, 0x3d800000, v91
	v_min_f32_e32 v41, 0, v44
	ds_read_b128 v[44:47], v55 offset:448
	ds_read_b128 v[94:97], v55 offset:464
	v_mul_f32_e32 v43, 0x3f317217, v93
	v_fma_f32 v43, v93, s57, -v43
	v_fmac_f32_e32 v43, 0x3377d1cf, v93
	s_waitcnt lgkmcnt(1)
	v_mul_f32_e32 v45, v85, v45
	v_fmac_f32_e32 v45, v84, v44
	v_fmac_f32_e32 v45, v74, v46
	v_fmac_f32_e32 v45, v75, v47
	v_add_f32_e32 v98, v87, v45
	s_waitcnt lgkmcnt(0)
	v_mul_f32_e32 v95, v72, v95
	ds_read_b128 v[44:47], v55 offset:480
	v_fmac_f32_e32 v95, v83, v94
	v_fmac_f32_e32 v95, v86, v96
	v_fmac_f32_e32 v95, v82, v97
	v_add_f32_e32 v98, v98, v95
	ds_read_b128 v[94:97], v55 offset:496
	s_waitcnt lgkmcnt(1)
	v_mul_f32_e32 v45, v1, v45
	v_fmac_f32_e32 v45, v66, v44
	v_fmac_f32_e32 v45, v69, v46
	v_fmac_f32_e32 v45, v61, v47
	v_add_f32_e32 v44, v98, v45
	s_waitcnt lgkmcnt(0)
	v_mul_f32_e32 v45, v60, v95
	v_fmac_f32_e32 v45, v63, v94
	v_fmac_f32_e32 v45, v65, v96
	v_fmac_f32_e32 v45, v62, v97
	v_add_f32_e32 v44, v44, v45
	v_mul_f32_e64 v45, |v44|, s53
	v_exp_f32_e32 v45, v45
	v_fmac_f32_e32 v43, 0x3f317217, v93
	v_cmp_lt_f32_e64 s[14:15], |v93|, s67
	v_cndmask_b32_e32 v46, 0, v81, vcc
	v_add_f32_e32 v45, 1.0, v45
	v_cndmask_b32_e64 v43, v93, v43, s[14:15]
	v_cmp_gt_f32_e32 vcc, s56, v45
	v_sub_f32_e32 v43, v43, v46
	v_sub_f32_e32 v41, v41, v43
	v_cndmask_b32_e64 v46, 0, 32, vcc
	v_ldexp_f32 v45, v45, v46
	v_log_f32_e32 v98, v45
	v_fmamk_f32 v93, v41, 0x3d800000, v92
	v_min_f32_e32 v41, 0, v44
	ds_read_b128 v[44:47], v55 offset:512
	ds_read_b128 v[94:97], v55 offset:528
	v_mul_f32_e32 v43, 0x3f317217, v98
	v_fma_f32 v43, v98, s57, -v43
	v_fmac_f32_e32 v43, 0x3377d1cf, v98
	s_waitcnt lgkmcnt(1)
; #define LAS __attribute__((address_space(3)))
; __device__ __forceinline__ void gates_compute(const GateIn& g, LAS float* aL, LAS float* tot, int tid, float (&bq)[16], float& blast) {
;     ...
;     float run = 0.f;
; #pragma unroll
;     for (int ii = 0; ii < 16; ++ii) { const LAS f32x4* ar = (const LAS f32x4*)(aL + (16 * ig + ii) * 16); float z = g.gb;
; #pragma unroll
;         for (int r4 = 0; r4 < 4; ++r4) { const f32x4 av = ar[r4]; z += av.x * g.w2r[4 * r4] + av.y * g.w2r[4 * r4 + 1] + av.z * g.w2r[4 * r4 + 2] + av.w * g.w2r[4 * r4 + 3]; }
;         const float ls = fminf(z, 0.f) - __logf(1.0f + __expf(-fabsf(z)));
;         run += ls * (1.0f / 16.0f); bq[ii] = run; }
	v_mul_f32_e32 v45, v85, v45
	v_fmac_f32_e32 v45, v84, v44
	v_fmac_f32_e32 v45, v74, v46
	v_fmac_f32_e32 v45, v75, v47
	v_add_f32_e32 v99, v87, v45
	s_waitcnt lgkmcnt(0)
	v_mul_f32_e32 v95, v72, v95
	ds_read_b128 v[44:47], v55 offset:544
	v_fmac_f32_e32 v95, v83, v94
	v_fmac_f32_e32 v95, v86, v96
	v_fmac_f32_e32 v95, v82, v97
	v_add_f32_e32 v99, v99, v95
	ds_read_b128 v[94:97], v55 offset:560
	s_waitcnt lgkmcnt(1)
	v_mul_f32_e32 v45, v1, v45
	v_fmac_f32_e32 v45, v66, v44
	v_fmac_f32_e32 v45, v69, v46
	v_fmac_f32_e32 v45, v61, v47
	v_add_f32_e32 v44, v99, v45
	s_waitcnt lgkmcnt(0)
	v_mul_f32_e32 v45, v60, v95
	v_fmac_f32_e32 v45, v63, v94
	v_fmac_f32_e32 v45, v65, v96
	v_fmac_f32_e32 v45, v62, v97
	v_add_f32_e32 v44, v44, v45
	v_mul_f32_e64 v45, |v44|, s53
	v_exp_f32_e32 v45, v45
	v_fmac_f32_e32 v43, 0x3f317217, v98
	v_cmp_lt_f32_e64 s[14:15], |v98|, s67
	v_cndmask_b32_e32 v46, 0, v81, vcc
	v_add_f32_e32 v45, 1.0, v45
	v_cndmask_b32_e64 v43, v98, v43, s[14:15]
	v_cmp_gt_f32_e32 vcc, s56, v45
	v_sub_f32_e32 v43, v43, v46
	v_sub_f32_e32 v41, v41, v43
	v_cndmask_b32_e64 v46, 0, 32, vcc
	v_ldexp_f32 v45, v45, v46
	v_log_f32_e32 v95, v45
	v_fmamk_f32 v94, v41, 0x3d800000, v93
	v_min_f32_e32 v41, 0, v44
	ds_read_b128 v[44:47], v55 offset:576
	ds_read_b128 v[96:99], v55 offset:592
	v_mul_f32_e32 v43, 0x3f317217, v95
	v_fma_f32 v43, v95, s57, -v43
	v_fmac_f32_e32 v43, 0x3377d1cf, v95
	s_waitcnt lgkmcnt(1)
	v_mul_f32_e32 v45, v85, v45
	v_fmac_f32_e32 v45, v84, v44
	v_fmac_f32_e32 v45, v74, v46
	v_fmac_f32_e32 v45, v75, v47
	v_add_f32_e32 v100, v87, v45
	s_waitcnt lgkmcnt(0)
	v_mul_f32_e32 v97, v72, v97
	ds_read_b128 v[44:47], v55 offset:608
	v_fmac_f32_e32 v97, v83, v96
	v_fmac_f32_e32 v97, v86, v98
	v_fmac_f32_e32 v97, v82, v99
	v_add_f32_e32 v100, v100, v97
	ds_read_b128 v[96:99], v55 offset:624
	s_waitcnt lgkmcnt(1)
	v_mul_f32_e32 v45, v1, v45
	v_fmac_f32_e32 v45, v66, v44
	v_fmac_f32_e32 v45, v69, v46
	v_fmac_f32_e32 v45, v61, v47
	v_add_f32_e32 v44, v100, v45
	s_waitcnt lgkmcnt(0)
	v_mul_f32_e32 v45, v60, v97
	v_fmac_f32_e32 v45, v63, v96
	v_fmac_f32_e32 v45, v65, v98
	v_fmac_f32_e32 v45, v62, v99
	v_add_f32_e32 v44, v44, v45
	v_mul_f32_e64 v45, |v44|, s53
	v_exp_f32_e32 v45, v45
	v_fmac_f32_e32 v43, 0x3f317217, v95
	v_cmp_lt_f32_e64 s[14:15], |v95|, s67
	v_cndmask_b32_e32 v46, 0, v81, vcc
	v_add_f32_e32 v45, 1.0, v45
	v_cndmask_b32_e64 v43, v95, v43, s[14:15]
	v_cmp_gt_f32_e32 vcc, s56, v45
	v_sub_f32_e32 v43, v43, v46
	v_sub_f32_e32 v41, v41, v43
	v_cndmask_b32_e64 v46, 0, 32, vcc
	v_ldexp_f32 v45, v45, v46
	v_log_f32_e32 v100, v45
	v_fmamk_f32 v95, v41, 0x3d800000, v94
	v_min_f32_e32 v41, 0, v44
	ds_read_b128 v[44:47], v55 offset:640
	ds_read_b128 v[96:99], v55 offset:656
	v_mul_f32_e32 v43, 0x3f317217, v100
	v_fma_f32 v43, v100, s57, -v43
	v_fmac_f32_e32 v43, 0x3377d1cf, v100
	s_waitcnt lgkmcnt(1)
	v_mul_f32_e32 v45, v85, v45
	v_fmac_f32_e32 v45, v84, v44
	v_fmac_f32_e32 v45, v74, v46
	v_fmac_f32_e32 v45, v75, v47
	v_add_f32_e32 v101, v87, v45
	s_waitcnt lgkmcnt(0)
	v_mul_f32_e32 v97, v72, v97
	ds_read_b128 v[44:47], v55 offset:672
	v_fmac_f32_e32 v97, v83, v96
	v_fmac_f32_e32 v97, v86, v98
	v_fmac_f32_e32 v97, v82, v99
	v_add_f32_e32 v101, v101, v97
	ds_read_b128 v[96:99], v55 offset:688
	s_waitcnt lgkmcnt(1)
	v_mul_f32_e32 v45, v1, v45
	v_fmac_f32_e32 v45, v66, v44
	v_fmac_f32_e32 v45, v69, v46
	v_fmac_f32_e32 v45, v61, v47
	v_add_f32_e32 v44, v101, v45
	s_waitcnt lgkmcnt(0)
	v_mul_f32_e32 v45, v60, v97
	v_fmac_f32_e32 v45, v63, v96
	v_fmac_f32_e32 v45, v65, v98
	v_fmac_f32_e32 v45, v62, v99
	v_add_f32_e32 v44, v44, v45
	v_mul_f32_e64 v45, |v44|, s53
	v_exp_f32_e32 v45, v45
	v_fmac_f32_e32 v43, 0x3f317217, v100
	v_cmp_lt_f32_e64 s[14:15], |v100|, s67
	v_cndmask_b32_e32 v46, 0, v81, vcc
	v_add_f32_e32 v45, 1.0, v45
	v_cndmask_b32_e64 v43, v100, v43, s[14:15]
	v_cmp_gt_f32_e32 vcc, s56, v45
	v_sub_f32_e32 v43, v43, v46
	v_sub_f32_e32 v41, v41, v43
	v_cndmask_b32_e64 v46, 0, 32, vcc
	v_ldexp_f32 v45, v45, v46
	v_log_f32_e32 v97, v45
	v_fmamk_f32 v96, v41, 0x3d800000, v95
	v_min_f32_e32 v41, 0, v44
	ds_read_b128 v[44:47], v55 offset:704
	ds_read_b128 v[98:101], v55 offset:720
	v_mul_f32_e32 v43, 0x3f317217, v97
	v_fma_f32 v43, v97, s57, -v43
	v_fmac_f32_e32 v43, 0x3377d1cf, v97
	s_waitcnt lgkmcnt(1)
	v_mul_f32_e32 v45, v85, v45
	v_fmac_f32_e32 v45, v84, v44
	v_fmac_f32_e32 v45, v74, v46
	v_fmac_f32_e32 v45, v75, v47
	v_add_f32_e32 v102, v87, v45
	s_waitcnt lgkmcnt(0)
	v_mul_f32_e32 v99, v72, v99
	ds_read_b128 v[44:47], v55 offset:736
	v_fmac_f32_e32 v99, v83, v98
	v_fmac_f32_e32 v99, v86, v100
	v_fmac_f32_e32 v99, v82, v101
	v_add_f32_e32 v102, v102, v99
	ds_read_b128 v[98:101], v55 offset:752
	s_waitcnt lgkmcnt(1)
	v_mul_f32_e32 v45, v1, v45
	v_fmac_f32_e32 v45, v66, v44
	v_fmac_f32_e32 v45, v69, v46
	v_fmac_f32_e32 v45, v61, v47
	v_add_f32_e32 v44, v102, v45
	s_waitcnt lgkmcnt(0)
	v_mul_f32_e32 v45, v60, v99
	v_fmac_f32_e32 v45, v63, v98
	v_fmac_f32_e32 v45, v65, v100
	v_fmac_f32_e32 v45, v62, v101
	v_add_f32_e32 v44, v44, v45
	v_mul_f32_e64 v45, |v44|, s53
	v_exp_f32_e32 v45, v45
	v_fmac_f32_e32 v43, 0x3f317217, v97
	v_cmp_lt_f32_e64 s[14:15], |v97|, s67
	v_cndmask_b32_e32 v46, 0, v81, vcc
	v_add_f32_e32 v45, 1.0, v45
	v_cndmask_b32_e64 v43, v97, v43, s[14:15]
	v_cmp_gt_f32_e32 vcc, s56, v45
	v_sub_f32_e32 v43, v43, v46
	v_sub_f32_e32 v41, v41, v43
	v_cndmask_b32_e64 v46, 0, 32, vcc
	v_ldexp_f32 v45, v45, v46
	v_log_f32_e32 v102, v45
	v_fmamk_f32 v97, v41, 0x3d800000, v96
	v_min_f32_e32 v41, 0, v44
	ds_read_b128 v[44:47], v55 offset:768
	ds_read_b128 v[98:101], v55 offset:784
	v_mul_f32_e32 v43, 0x3f317217, v102
	v_fma_f32 v43, v102, s57, -v43
	v_fmac_f32_e32 v43, 0x3377d1cf, v102
	s_waitcnt lgkmcnt(1)
; #define LAS __attribute__((address_space(3)))
; __device__ __forceinline__ void gates_compute(const GateIn& g, LAS float* aL, LAS float* tot, int tid, float (&bq)[16], float& blast) {
;     ...
;         run += ls * (1.0f / 16.0f); bq[ii] = run; }
;     tot[ig * 128 + d] = run;
;     __syncthreads();
;     float off = 0.f, all = 0.f;
; #pragma unroll
;     for (int gg = 0; gg < 4; ++gg) { const float t = tot[gg * 128 + d]; all += t; off += (gg < ig) ? t : 0.f; }
; #pragma unroll
;     for (int ii = 0; ii < 16; ++ii) bq[ii] += off;
;     blast = all;
; __device__ __forceinline__ void phase_g1(const Args& a, LAS unsigned char* lds, int tid, int lane, int wave) {
;     ...
;         for (int s2 = 0; s2 < 2; ++s2) { const int c = tid + 512 * s2; *(LAS v4u*)(Kr + (c >> 4) * 136 + 8 * (c & 15)) = kreg[s2]; }
; #pragma unroll
;         for (int s4 = 0; s4 < 4; ++s4) { const int c = tid + 512 * s4; *(LAS v4u*)(Vs + (c >> 5) * 264 + 8 * (c & 31)) = vreg[s4]; }
;         { const int nu = unit + (int)gridDim.x; if (nu < 2048) G1_LOADS(nu); }
	v_mul_f32_e32 v45, v85, v45
	v_fmac_f32_e32 v45, v84, v44
	v_fmac_f32_e32 v45, v74, v46
	v_fmac_f32_e32 v45, v75, v47
	v_add_f32_e32 v103, v87, v45
	s_waitcnt lgkmcnt(0)
	v_mul_f32_e32 v99, v72, v99
	ds_read_b128 v[44:47], v55 offset:800
	v_fmac_f32_e32 v99, v83, v98
	v_fmac_f32_e32 v99, v86, v100
	v_fmac_f32_e32 v99, v82, v101
	v_add_f32_e32 v103, v103, v99
	ds_read_b128 v[98:101], v55 offset:816
	s_waitcnt lgkmcnt(1)
	v_mul_f32_e32 v45, v1, v45
	v_fmac_f32_e32 v45, v66, v44
	v_fmac_f32_e32 v45, v69, v46
	v_fmac_f32_e32 v45, v61, v47
	v_add_f32_e32 v44, v103, v45
	s_waitcnt lgkmcnt(0)
	v_mul_f32_e32 v45, v60, v99
	v_fmac_f32_e32 v45, v63, v98
	v_fmac_f32_e32 v45, v65, v100
	v_fmac_f32_e32 v45, v62, v101
	v_add_f32_e32 v44, v44, v45
	v_mul_f32_e64 v45, |v44|, s53
	v_exp_f32_e32 v45, v45
	v_fmac_f32_e32 v43, 0x3f317217, v102
	v_cmp_lt_f32_e64 s[14:15], |v102|, s67
	v_cndmask_b32_e32 v46, 0, v81, vcc
	v_add_f32_e32 v45, 1.0, v45
	v_cndmask_b32_e64 v43, v102, v43, s[14:15]
	v_cmp_gt_f32_e32 vcc, s56, v45
	v_sub_f32_e32 v43, v43, v46
	v_sub_f32_e32 v41, v41, v43
	v_cndmask_b32_e64 v46, 0, 32, vcc
	v_ldexp_f32 v45, v45, v46
	v_log_f32_e32 v99, v45
	v_fmamk_f32 v98, v41, 0x3d800000, v97
	v_min_f32_e32 v41, 0, v44
	ds_read_b128 v[44:47], v55 offset:832
	ds_read_b128 v[100:103], v55 offset:848
	v_mul_f32_e32 v43, 0x3f317217, v99
	v_fma_f32 v43, v99, s57, -v43
	v_fmac_f32_e32 v43, 0x3377d1cf, v99
	s_waitcnt lgkmcnt(1)
	v_mul_f32_e32 v45, v85, v45
	v_fmac_f32_e32 v45, v84, v44
	v_fmac_f32_e32 v45, v74, v46
	v_fmac_f32_e32 v45, v75, v47
	v_add_f32_e32 v104, v87, v45
	s_waitcnt lgkmcnt(0)
	v_mul_f32_e32 v101, v72, v101
	ds_read_b128 v[44:47], v55 offset:864
	v_fmac_f32_e32 v101, v83, v100
	v_fmac_f32_e32 v101, v86, v102
	v_fmac_f32_e32 v101, v82, v103
	v_add_f32_e32 v104, v104, v101
	ds_read_b128 v[100:103], v55 offset:880
	s_waitcnt lgkmcnt(1)
	v_mul_f32_e32 v45, v1, v45
	v_fmac_f32_e32 v45, v66, v44
	v_fmac_f32_e32 v45, v69, v46
	v_fmac_f32_e32 v45, v61, v47
	v_add_f32_e32 v44, v104, v45
	s_waitcnt lgkmcnt(0)
	v_mul_f32_e32 v45, v60, v101
	v_fmac_f32_e32 v45, v63, v100
	v_fmac_f32_e32 v45, v65, v102
	v_fmac_f32_e32 v45, v62, v103
	v_add_f32_e32 v44, v44, v45
	v_mul_f32_e64 v45, |v44|, s53
	v_exp_f32_e32 v45, v45
	v_fmac_f32_e32 v43, 0x3f317217, v99
	v_cmp_lt_f32_e64 s[14:15], |v99|, s67
	v_cndmask_b32_e32 v46, 0, v81, vcc
	v_add_f32_e32 v45, 1.0, v45
	v_cndmask_b32_e64 v43, v99, v43, s[14:15]
	v_cmp_gt_f32_e32 vcc, s56, v45
	v_sub_f32_e32 v43, v43, v46
	v_sub_f32_e32 v41, v41, v43
	v_cndmask_b32_e64 v46, 0, 32, vcc
	v_ldexp_f32 v45, v45, v46
	v_log_f32_e32 v104, v45
	v_fmamk_f32 v99, v41, 0x3d800000, v98
	v_min_f32_e32 v41, 0, v44
	ds_read_b128 v[44:47], v55 offset:896
	ds_read_b128 v[100:103], v55 offset:912
	v_mul_f32_e32 v43, 0x3f317217, v104
	v_fma_f32 v43, v104, s57, -v43
	v_fmac_f32_e32 v43, 0x3377d1cf, v104
	s_waitcnt lgkmcnt(1)
	v_mul_f32_e32 v45, v85, v45
	v_fmac_f32_e32 v45, v84, v44
	v_fmac_f32_e32 v45, v74, v46
	v_fmac_f32_e32 v45, v75, v47
	v_add_f32_e32 v105, v87, v45
	s_waitcnt lgkmcnt(0)
	v_mul_f32_e32 v101, v72, v101
	ds_read_b128 v[44:47], v55 offset:928
	v_fmac_f32_e32 v101, v83, v100
	v_fmac_f32_e32 v101, v86, v102
	v_fmac_f32_e32 v101, v82, v103
	v_add_f32_e32 v105, v105, v101
	ds_read_b128 v[100:103], v55 offset:944
	s_waitcnt lgkmcnt(1)
	v_mul_f32_e32 v45, v1, v45
	v_fmac_f32_e32 v45, v66, v44
	v_fmac_f32_e32 v45, v69, v46
	v_fmac_f32_e32 v45, v61, v47
	v_add_f32_e32 v44, v105, v45
	s_waitcnt lgkmcnt(0)
	v_mul_f32_e32 v45, v60, v101
	v_fmac_f32_e32 v45, v63, v100
	v_fmac_f32_e32 v45, v65, v102
	v_fmac_f32_e32 v45, v62, v103
	v_add_f32_e32 v44, v44, v45
	v_mul_f32_e64 v45, |v44|, s53
	v_exp_f32_e32 v45, v45
	v_fmac_f32_e32 v43, 0x3f317217, v104
	v_cmp_lt_f32_e64 s[14:15], |v104|, s67
	v_cndmask_b32_e32 v46, 0, v81, vcc
	v_add_f32_e32 v45, 1.0, v45
	v_cndmask_b32_e64 v43, v104, v43, s[14:15]
	v_cmp_gt_f32_e32 vcc, s56, v45
	v_sub_f32_e32 v43, v43, v46
	v_sub_f32_e32 v41, v41, v43
	v_cndmask_b32_e64 v46, 0, 32, vcc
	v_ldexp_f32 v45, v45, v46
	v_log_f32_e32 v101, v45
	v_fmamk_f32 v100, v41, 0x3d800000, v99
	v_min_f32_e32 v41, 0, v44
	ds_read_b128 v[44:47], v55 offset:960
	ds_read_b128 v[102:105], v55 offset:976
	v_mul_f32_e32 v43, 0x3f317217, v101
	v_fma_f32 v43, v101, s57, -v43
	v_fmac_f32_e32 v43, 0x3377d1cf, v101
	s_waitcnt lgkmcnt(1)
	v_mul_f32_e32 v45, v85, v45
	v_fmac_f32_e32 v45, v84, v44
	v_fmac_f32_e32 v45, v74, v46
	v_fmac_f32_e32 v45, v75, v47
	v_add_f32_e32 v106, v87, v45
	s_waitcnt lgkmcnt(0)
	v_mul_f32_e32 v103, v72, v103
	ds_read_b128 v[44:47], v55 offset:992
	v_fmac_f32_e32 v103, v83, v102
	v_fmac_f32_e32 v103, v86, v104
	v_fmac_f32_e32 v103, v82, v105
	v_add_f32_e32 v106, v106, v103
	ds_read_b128 v[102:105], v55 offset:1008
	s_waitcnt lgkmcnt(1)
	v_mul_f32_e32 v45, v1, v45
	v_fmac_f32_e32 v45, v66, v44
	v_fmac_f32_e32 v45, v69, v46
	v_fmac_f32_e32 v45, v61, v47
	v_add_f32_e32 v44, v106, v45
	s_waitcnt lgkmcnt(0)
	v_mul_f32_e32 v45, v60, v103
	v_fmac_f32_e32 v45, v63, v102
	v_fmac_f32_e32 v45, v65, v104
	v_fmac_f32_e32 v45, v62, v105
	v_add_f32_e32 v44, v44, v45
	v_mul_f32_e64 v45, |v44|, s53
	v_exp_f32_e32 v45, v45
	v_fmac_f32_e32 v43, 0x3f317217, v101
	v_cmp_lt_f32_e64 s[14:15], |v101|, s67
	v_cndmask_b32_e32 v46, 0, v81, vcc
	v_add_f32_e32 v45, 1.0, v45
	v_cndmask_b32_e64 v43, v101, v43, s[14:15]
	v_cmp_gt_f32_e32 vcc, s56, v45
	v_sub_f32_e32 v43, v43, v46
	v_sub_f32_e32 v41, v41, v43
	v_cndmask_b32_e64 v46, 0, 32, vcc
	v_ldexp_f32 v45, v45, v46
	v_log_f32_e32 v45, v45
	v_fmamk_f32 v101, v41, 0x3d800000, v100
	v_min_f32_e32 v41, 0, v44
	v_cndmask_b32_e32 v44, 0, v81, vcc
	v_mul_f32_e32 v43, 0x3f317217, v45
	v_fma_f32 v43, v45, s57, -v43
	v_fmac_f32_e32 v43, 0x3377d1cf, v45
	v_fmac_f32_e32 v43, 0x3f317217, v45
	v_cmp_lt_f32_e64 s[14:15], |v45|, s67
	s_nop 1
	v_cndmask_b32_e64 v43, v45, v43, s[14:15]
	v_sub_f32_e32 v43, v43, v44
	v_sub_f32_e32 v41, v41, v43
	v_fmamk_f32 v102, v41, 0x3d800000, v101
	ds_write_b32 v56, v102 offset:4096
	s_waitcnt lgkmcnt(0)
	s_barrier
	ds_read2st64_b32 v[46:47], v57 offset0:16 offset1:18
	ds_read2st64_b32 v[44:45], v57 offset0:20 offset1:22
	s_cselect_b64 s[14:15], -1, 0
	s_and_b64 vcc, exec, s[14:15]
	ds_write_b128 v67, v[10:13] offset:26624
	ds_write_b128 v68, v[6:9] offset:26624
	ds_write_b128 v70, v[18:21] offset:44032
	ds_write_b128 v71, v[14:17] offset:44032
	ds_write_b128 v70, v[26:29] offset:60928
	ds_write_b128 v73, v[22:25] offset:44032
	s_cbranch_vccnz .LBB0_290
	v_mov_b32_e32 v2, v0
	v_mov_b32_e32 v3, v0
	s_and_b32 s22, s49, 0xffffc000
	s_and_b32 s27, s51, 0x3fc0
	v_mov_b32_e32 v1, v0
	v_mov_b64_e32 v[4:5], v[2:3]
	s_or_b32 s28, s22, s27
	v_mov_b64_e32 v[2:3], v[0:1]
	s_and_saveexec_b64 s[30:31], s[4:5]
	s_cbranch_execz .LBB0_289
	s_ashr_i32 s29, s28, 31
	s_lshl_b64 s[76:77], s[28:29], 6
	v_lshl_add_u64 v[2:3], v[36:37], 0, s[76:77]
	global_load_dwordx4 v[2:5], v[2:3], off
